# grid barriers: non-last XCD leaders also use the 3-deep pipelined generation poll
# baseline (speedup 1.0000x reference)
; __device__ __forceinline__ unsigned xb_ld(unsigned* p)              { return __hip_atomic_load(p, __ATOMIC_RELAXED, __HIP_MEMORY_SCOPE_AGENT); }
; __device__ __forceinline__ unsigned xb_add(unsigned* p, unsigned v) { return __hip_atomic_fetch_add(p, v, __ATOMIC_RELAXED, __HIP_MEMORY_SCOPE_AGENT); }
; #define XB_SPIN(cond, bar) do { unsigned _sp = 0; while (cond) { __builtin_amdgcn_s_sleep(1); \
;     if ((++_sp & 255u) == 0u) { if (xb_ld(&(bar)[XB_TMO])) break; if (_sp > XB_SPIN_CAP) { atomicAdd(&(bar)[XB_TMO], 1u); break; } } } } while (0)
; __device__ __forceinline__ void xcd_barrier(const XcdBarrier& b) {
;     ...
;             const unsigned tg = og / nx;
;             if (og + 1u == (tg + 1u) * nx) xb_add(&bar[XB_TOPGEN], 1u);
;             else XB_SPIN(xb_ld(&bar[XB_TOPGEN]) == tg, bar);
.LBB0_105:
	s_or_b64 exec, exec, s[8:9]
	v_cvt_f32_u32_e32 v3, v0
	s_waitcnt vmcnt(0)
	v_readfirstlane_b32 s6, v2
	s_add_u32 s8, s96, 0x183500
	s_addc_u32 s9, s97, 0
	v_rcp_iflag_f32_e32 v3, v3
	v_add_u32_e32 v1, s6, v1
	v_add_u32_e32 v4, 1, v1
	s_mov_b64 s[10:11], -1
	v_mul_f32_e32 v2, 0x4f7ffffe, v3
	v_cvt_u32_f32_e32 v2, v2
	v_sub_u32_e32 v3, 0, v0
	v_mul_lo_u32 v3, v3, v2
	v_mul_hi_u32 v3, v2, v3
	v_add_u32_e32 v2, v2, v3
	v_mul_hi_u32 v2, v1, v2
	v_mul_lo_u32 v3, v2, v0
	v_sub_u32_e32 v1, v1, v3
	v_add_u32_e32 v5, 1, v2
	v_cmp_ge_u32_e32 vcc, v1, v0
	v_sub_u32_e32 v3, v1, v0
	s_nop 0
	v_cndmask_b32_e32 v2, v2, v5, vcc
	v_cndmask_b32_e32 v1, v1, v3, vcc
	v_add_u32_e32 v3, 1, v2
	v_cmp_ge_u32_e32 vcc, v1, v0
	s_nop 1
	v_cndmask_b32_e32 v2, v2, v3, vcc
	v_mul_lo_u32 v1, v0, v2
	v_add_u32_e32 v0, v1, v0
	v_cmp_ne_u32_e32 vcc, v4, v0
	v_mov_b64_e32 v[0:1], s[8:9]
	s_and_saveexec_b64 s[6:7], vcc
	s_cbranch_execz .LBB0_117
	v_mov_b32_e32 v0, 0
	s_mov_b32 s24, 0x100000
	global_load_dword v120, v0, s[8:9] sc1
	s_sleep 5
	global_load_dword v121, v0, s[8:9] sc1
	s_sleep 5
.Lpl_l1_loop:
	global_load_dword v122, v0, s[8:9] sc1
	s_waitcnt vmcnt(2)
	v_cmp_ne_u32_e32 vcc, v120, v2
	s_cbranch_vccnz .Lpl_l1_done
	s_sleep 5
	global_load_dword v120, v0, s[8:9] sc1
	s_waitcnt vmcnt(2)
	v_cmp_ne_u32_e32 vcc, v121, v2
	s_cbranch_vccnz .Lpl_l1_done
	s_sleep 5
	global_load_dword v121, v0, s[8:9] sc1
	s_waitcnt vmcnt(2)
	v_cmp_ne_u32_e32 vcc, v122, v2
	s_cbranch_vccnz .Lpl_l1_done
	s_sleep 5
	s_sub_i32 s24, s24, 1
	s_cmp_lg_u32 s24, 0
	s_cbranch_scc1 .Lpl_l1_loop
.Lpl_l1_done:
	s_mov_b64 s[10:11], 0

; __device__ __forceinline__ unsigned xb_ld(unsigned* p)              { return __hip_atomic_load(p, __ATOMIC_RELAXED, __HIP_MEMORY_SCOPE_AGENT); }
; __device__ __forceinline__ unsigned xb_add(unsigned* p, unsigned v) { return __hip_atomic_fetch_add(p, v, __ATOMIC_RELAXED, __HIP_MEMORY_SCOPE_AGENT); }
; #define XB_SPIN(cond, bar) do { unsigned _sp = 0; while (cond) { __builtin_amdgcn_s_sleep(1); \
;     if ((++_sp & 255u) == 0u) { if (xb_ld(&(bar)[XB_TMO])) break; if (_sp > XB_SPIN_CAP) { atomicAdd(&(bar)[XB_TMO], 1u); break; } } } } while (0)
; __device__ __forceinline__ void xcd_barrier(const XcdBarrier& b) {
;     ...
;             const unsigned tg = og / nx;
;             if (og + 1u == (tg + 1u) * nx) xb_add(&bar[XB_TOPGEN], 1u);
;             else XB_SPIN(xb_ld(&bar[XB_TOPGEN]) == tg, bar);
.LBB0_374:
	s_or_b64 exec, exec, s[6:7]
	v_cvt_f32_u32_e32 v3, v0
	s_waitcnt vmcnt(0)
	v_readfirstlane_b32 s4, v2
	s_add_u32 s6, s96, 0x183500
	s_addc_u32 s7, s97, 0
	v_rcp_iflag_f32_e32 v3, v3
	v_add_u32_e32 v1, s4, v1
	v_add_u32_e32 v4, 1, v1
	s_mov_b64 s[8:9], -1
	v_mul_f32_e32 v2, 0x4f7ffffe, v3
	v_cvt_u32_f32_e32 v2, v2
	v_sub_u32_e32 v3, 0, v0
	v_mul_lo_u32 v3, v3, v2
	v_mul_hi_u32 v3, v2, v3
	v_add_u32_e32 v2, v2, v3
	v_mul_hi_u32 v2, v1, v2
	v_mul_lo_u32 v3, v2, v0
	v_sub_u32_e32 v1, v1, v3
	v_add_u32_e32 v5, 1, v2
	v_cmp_ge_u32_e32 vcc, v1, v0
	v_sub_u32_e32 v3, v1, v0
	s_nop 0
	v_cndmask_b32_e32 v2, v2, v5, vcc
	v_cndmask_b32_e32 v1, v1, v3, vcc
	v_add_u32_e32 v3, 1, v2
	v_cmp_ge_u32_e32 vcc, v1, v0
	s_nop 1
	v_cndmask_b32_e32 v2, v2, v3, vcc
	v_mul_lo_u32 v1, v0, v2
	v_add_u32_e32 v0, v1, v0
	v_cmp_ne_u32_e32 vcc, v4, v0
	v_mov_b64_e32 v[0:1], s[6:7]
	s_and_saveexec_b64 s[4:5], vcc
	s_cbranch_execz .LBB0_386
	v_mov_b32_e32 v0, 0
	s_mov_b32 s22, 0x100000
	global_load_dword v120, v0, s[6:7] sc1
	s_sleep 5
	global_load_dword v121, v0, s[6:7] sc1
	s_sleep 5
.Lpl_l2_loop:
	global_load_dword v122, v0, s[6:7] sc1
	s_waitcnt vmcnt(2)
	v_cmp_ne_u32_e32 vcc, v120, v2
	s_cbranch_vccnz .Lpl_l2_done
	s_sleep 5
	global_load_dword v120, v0, s[6:7] sc1
	s_waitcnt vmcnt(2)
	v_cmp_ne_u32_e32 vcc, v121, v2
	s_cbranch_vccnz .Lpl_l2_done
	s_sleep 5
	global_load_dword v121, v0, s[6:7] sc1
	s_waitcnt vmcnt(2)
	v_cmp_ne_u32_e32 vcc, v122, v2
	s_cbranch_vccnz .Lpl_l2_done
	s_sleep 5
	s_sub_i32 s22, s22, 1
	s_cmp_lg_u32 s22, 0
	s_cbranch_scc1 .Lpl_l2_loop
.Lpl_l2_done:
	s_mov_b64 s[8:9], 0
